# v28 + GEMM phase prologues: K-tile 1 LDS-DMA loads issued before the wait for K-tile 0 (prologue de-serialisation)
# baseline (speedup 1.0000x reference)
.LBB0_319:
	v_readlane_b32 s20, v254, 19
	v_readlane_b32 s21, v254, 20
	s_add_u32 s48, s20, 0x39a00000
	s_addc_u32 s49, s21, 0
	s_add_u32 s78, s20, 0x3e200000
	s_addc_u32 s79, s21, 0
	s_add_u32 s82, s20, 0x3fa00000
	s_addc_u32 s83, s21, 0
	s_add_u32 s86, s20, 0x41200000
	s_addc_u32 s87, s21, 0
	s_add_u32 s90, s20, 0x42a00000
	s_addc_u32 s91, s21, 0
	s_add_u32 s94, s20, 0x44200000
	s_addc_u32 s95, s21, 0
	s_add_u32 s6, s20, 0x28c00000
	s_addc_u32 s7, s21, 0
	v_writelane_b32 v254, s6, 29
	v_readlane_b32 s16, v253, 63
	s_lshl_b32 s8, s65, 10
	v_writelane_b32 v254, s7, 30
	v_lshl_add_u64 v[6:7], v[6:7], 0, s[96:97]
	v_readlane_b32 s17, v254, 0
	s_mov_b32 s1, s17
	v_readlane_b32 s18, v254, 1
	v_readlane_b32 s19, v254, 2
	s_mov_b32 s9, s17
	v_writelane_b32 v253, s0, 63
	s_lshl_b64 s[6:7], s[8:9], 2
	v_writelane_b32 v254, s1, 0
	v_writelane_b32 v254, s2, 1
	v_writelane_b32 v254, s3, 2
	s_add_u32 s1, s20, s6
	s_addc_u32 s5, s21, s7
	s_add_u32 s6, s1, 0x200000
	s_addc_u32 s7, s5, 0
	s_and_b32 s5, s4, 3
	s_add_i32 m0, s59, 0x18000
	v_writelane_b32 v254, s6, 31
	s_lshl_b32 s11, s0, 6
	s_lshl_b32 s15, s5, 5
	global_load_lds_dwordx4 v[6:7], off
	v_lshl_add_u64 v[4:5], v[4:5], 0, s[96:97]
	s_add_i32 m0, s59, 0x1a000
	s_add_i32 s12, s59, 0x8000
	s_add_i32 s13, s59, 0xa000
	v_writelane_b32 v254, s7, 32
	global_load_lds_dwordx4 v[4:5], off
	v_lshl_add_u64 v[0:1], v[0:1], 0, s[96:97]
	s_mov_b32 m0, s12
	s_add_u32 s6, s24, 0x80080
	global_load_lds_dwordx4 v[0:1], off
	v_lshl_add_u64 v[0:1], v[2:3], 0, s[96:97]
	s_mov_b32 m0, s13
	s_addc_u32 s7, s25, 0
	global_load_lds_dwordx4 v[0:1], off
	s_add_i32 m0, s59, 0x1c000
	v_lshl_add_u64 v[0:1], s[6:7], 0, v[174:175]
	global_load_lds_dwordx4 v[0:1], off
	v_lshl_add_u64 v[0:1], s[6:7], 0, v[176:177]
	s_add_i32 m0, s59, 0x1e000
	s_cmp_lt_u32 s4, 4
	global_load_lds_dwordx4 v[0:1], off
	s_waitcnt vmcnt(8)
	s_barrier
	v_and_b32_e32 v1, 0xfffffc00, v15
	v_lshl_add_u32 v2, s0, 13, v1
	v_lshl_add_u32 v1, s5, 12, v1
	s_cselect_b64 s[0:1], -1, 0
	s_lshl_b32 s5, s5, 4
	s_mov_b32 s35, s5
	s_or_b32 s5, s5, s15
	s_and_b32 s5, s5, 0x50
	v_writelane_b32 v254, s5, 33
	s_bfe_u32 s5, s4, 0x10001
	v_writelane_b32 v254, s5, 35
	s_and_b32 s4, s4, 1
	v_writelane_b32 v254, s4, 36
	s_and_b32 s4, s15, 32
	s_ashr_i32 s33, s57, 31
	s_ashr_i32 s84, s2, 31
	v_writelane_b32 v254, s4, 37
	s_cmpk_eq_i32 s57, 0xd8
	s_mov_b32 s4, 0x251a3
	s_cselect_b32 s4, s4, 0x7099
	v_writelane_b32 v254, s4, 38
	s_mov_b32 s4, 0x5074a873
	s_cselect_b32 s4, s4, 0x98f3aa8b
	v_writelane_b32 v254, s4, 39
	s_mov_b32 s4, 0x292a201
	v_and_b32_e32 v65, 15, v8
	v_and_b32_e32 v0, 48, v8
	v_lshlrev_b32_e32 v3, 2, v8
	s_cselect_b32 s4, s4, 0x24516b
	v_lshl_or_b32 v0, v65, 6, v0
	v_and_b32_e32 v3, 32, v3
	v_writelane_b32 v254, s4, 40
	s_mov_b32 s4, 0x96c0bdd0
	v_bitop3_b32 v2, v0, v2, v3 bitop3:0xde
	v_bitop3_b32 v201, v0, v1, v3 bitop3:0xde
	s_cselect_b32 s4, s4, 0xab2410a1
	v_lshlrev_b32_e32 v0, 15, v9
	v_writelane_b32 v254, s4, 41
	s_add_u32 s4, s20, 0x3ee00000
	v_and_b32_e32 v0, 0xffff0000, v0
	s_addc_u32 s5, s21, 0
	v_lshl_add_u32 v0, v10, 12, v0
	v_and_b32_e32 v1, 1, v9
	s_add_u32 s6, s20, 0x40600000
	v_lshl_or_b32 v0, v1, 6, v0
	s_addc_u32 s7, s21, 0
	v_lshl_add_u32 v178, v11, 1, v0
	v_lshlrev_b32_e32 v0, 15, v12
	s_add_u32 s8, s20, 0x44380000
	v_and_b32_e32 v0, 0xffff0000, v0
	s_waitcnt vmcnt(6)
	s_addc_u32 s9, s21, 0
	v_lshl_add_u32 v0, v13, 12, v0
	v_and_b32_e32 v1, 1, v12
	v_writelane_b32 v254, s15, 42
	s_lshl_b32 s16, s15, 1
	v_lshl_or_b32 v0, v1, 6, v0
	v_writelane_b32 v254, s16, 44
	v_ashrrev_i32_e32 v200, 4, v8
	v_mov_b32_e32 v179, v64
	v_lshl_add_u32 v180, v14, 1, v0
	v_mov_b32_e32 v181, v64
	s_mov_b32 s85, 0
	v_add_u32_e32 v202, 0, v2
	v_writelane_b32 v254, s17, 45
	s_mov_b32 s34, s72
	s_barrier
	s_branch .LBB0_322

.LBB0_890:
	s_add_u32 s69, s67, 0x104000
	s_sext_i32_i8 s86, s10
	s_addc_u32 s70, s68, 0
	s_lshl_b32 s10, s11, 5
	v_ashrrev_i32_e32 v15, 6, v14
	s_and_b32 s80, s10, 0x60
	s_add_i32 m0, s63, 0x18000
	v_lshl_add_u64 v[6:7], v[6:7], 0, s[96:97]
	s_lshl_b32 s73, s16, 6
	v_lshlrev_b32_e32 v17, 10, v15
	s_lshr_b32 s10, s80, 3
	global_load_lds_dwordx4 v[6:7], off
	v_lshl_add_u64 v[4:5], v[4:5], 0, s[96:97]
	s_add_i32 m0, s63, 0x1a000
	s_add_i32 s82, s63, 0x8000
	s_add_i32 s83, s63, 0xa000
	v_lshl_add_u32 v17, s16, 13, v17
	global_load_lds_dwordx4 v[4:5], off
	v_lshl_add_u64 v[0:1], v[0:1], 0, s[96:97]
	s_mov_b32 m0, s82
	s_add_u32 s16, s24, 0x80080
	global_load_lds_dwordx4 v[0:1], off
	v_lshl_add_u64 v[0:1], v[2:3], 0, s[96:97]
	s_mov_b32 m0, s83
	s_addc_u32 s17, s25, 0
	global_load_lds_dwordx4 v[0:1], off
	s_add_i32 m0, s63, 0x1c000
	v_lshl_add_u64 v[0:1], s[16:17], 0, v[160:161]
	global_load_lds_dwordx4 v[0:1], off
	v_lshl_add_u64 v[0:1], s[16:17], 0, v[176:177]
	s_add_i32 m0, s63, 0x1e000
	v_ashrrev_i32_e32 v65, 4, v14
	global_load_lds_dwordx4 v[0:1], off
	s_waitcnt vmcnt(8)
	s_barrier
	v_lshlrev_b32_e32 v0, 15, v8
	v_and_b32_e32 v0, 0xffff0000, v0
	v_lshl_add_u32 v0, v9, 12, v0
	v_and_b32_e32 v1, 1, v8
	v_lshl_or_b32 v0, v1, 6, v0
	v_lshl_add_u32 v178, v10, 1, v0
	v_lshlrev_b32_e32 v0, 15, v11
	v_and_b32_e32 v199, 15, v14
	v_and_b32_e32 v16, 48, v14
	v_lshlrev_b32_e32 v14, 2, v14
	v_and_b32_e32 v0, 0xffff0000, v0
	v_lshl_or_b32 v16, v199, 6, v16
	v_and_b32_e32 v14, 32, v14
	s_waitcnt vmcnt(6)
	v_lshl_add_u32 v0, v12, 12, v0
	v_and_b32_e32 v1, 1, v11
	v_bitop3_b32 v17, v16, v17, v14 bitop3:0xde
	v_add_lshl_u32 v15, s10, v15, 10
	s_cmp_lt_u32 s11, 4
	v_lshl_or_b32 v0, v1, 6, v0
	v_bitop3_b32 v225, v15, v16, v14 bitop3:0xf6
	s_cselect_b64 s[40:41], -1, 0
	s_ashr_i32 s84, s72, 31
	v_mov_b32_e32 v179, v64
	v_lshl_add_u32 v180, v13, 1, v0
	v_mov_b32_e32 v181, v64
	s_mov_b32 s85, 0
	v_add_u32_e32 v226, 0, v17
	s_barrier
	s_branch .LBB0_893

.LBB0_913:
	v_ashrrev_i32_e32 v14, 6, v65
	v_lshlrev_b32_e32 v16, 10, v14
	s_lshl_b32 s54, s18, 6
	v_lshl_add_u32 v16, s18, 13, v16
	s_lshl_b32 s18, s33, 5
	s_and_b32 s25, s18, 0x60
	s_add_i32 m0, s44, 0x18000
	v_lshl_add_u64 v[6:7], v[6:7], 0, s[96:97]
	s_lshr_b32 s18, s25, 3
	global_load_lds_dwordx4 v[6:7], off
	v_lshl_add_u64 v[4:5], v[4:5], 0, s[96:97]
	s_add_i32 m0, s44, 0x1a000
	s_add_i32 s55, s44, 0x8000
	s_add_i32 s58, s44, 0xa000
	global_load_lds_dwordx4 v[4:5], off
	v_lshl_add_u64 v[2:3], v[2:3], 0, s[96:97]
	s_mov_b32 m0, s55
	s_add_u32 s22, s8, 0x80080
	global_load_lds_dwordx4 v[2:3], off
	v_lshl_add_u64 v[0:1], v[0:1], 0, s[96:97]
	s_mov_b32 m0, s58
	s_addc_u32 s23, s9, 0
	global_load_lds_dwordx4 v[0:1], off
	s_add_i32 m0, s44, 0x1c000
	v_lshl_add_u64 v[0:1], s[22:23], 0, v[132:133]
	global_load_lds_dwordx4 v[0:1], off
	v_lshl_add_u64 v[0:1], s[22:23], 0, v[136:137]
	s_add_i32 m0, s44, 0x1e000
	v_add_lshl_u32 v14, s18, v14, 10
	global_load_lds_dwordx4 v[0:1], off
	s_waitcnt vmcnt(8)
	s_barrier
	s_lshl_b32 s18, s19, 17
	s_and_b32 s18, s18, 0x800000
	s_lshl_b32 s19, s20, 20
	s_or_b32 s18, s18, s19
	s_add_u32 s18, s78, s18
	v_lshlrev_b32_e32 v0, 15, v8
	s_addc_u32 s19, s79, 0
	v_and_b32_e32 v0, 0xffff0000, v0
	s_add_u32 s16, s18, s16
	v_lshl_add_u32 v0, v9, 12, v0
	v_and_b32_e32 v1, 1, v8
	s_addc_u32 s17, s19, s17
	v_lshl_or_b32 v0, v1, 6, v0
	s_add_u32 s16, s16, 0x1d480080
	v_lshl_add_u32 v0, v11, 1, v0
	v_mov_b32_e32 v1, v64
	s_addc_u32 s17, s17, 0
	v_lshl_add_u64 v[138:139], s[16:17], 0, v[0:1]
	v_lshlrev_b32_e32 v0, 15, v10
	v_and_b32_e32 v0, 0xffff0000, v0
	v_lshl_add_u32 v0, v12, 12, v0
	v_and_b32_e32 v1, 1, v10
	v_and_b32_e32 v142, 15, v65
	v_and_b32_e32 v15, 48, v65
	v_lshlrev_b32_e32 v17, 2, v65
	v_lshl_or_b32 v0, v1, 6, v0
	v_lshl_or_b32 v15, v142, 6, v15
	v_and_b32_e32 v17, 32, v17
	s_waitcnt vmcnt(6)
	v_lshl_add_u32 v0, v13, 1, v0
	v_mov_b32_e32 v1, v64
	v_bitop3_b32 v16, v15, v16, v17 bitop3:0xde
	v_lshl_add_u64 v[140:141], s[16:17], 0, v[0:1]
	v_mov_b32_e32 v0, 0
	v_bitop3_b32 v143, v14, v15, v17 bitop3:0xf6
	s_mov_b32 s59, -2
	s_mov_b64 s[16:17], 0
	v_add_u32_e32 v144, 0, v16
	v_mov_b32_e32 v1, v0
	v_mov_b32_e32 v2, v0
	v_mov_b32_e32 v3, v0
	v_mov_b32_e32 v4, v0
	v_mov_b32_e32 v5, v0
	v_mov_b32_e32 v6, v0
	v_mov_b32_e32 v7, v0
	v_mov_b32_e32 v8, v0
	v_mov_b32_e32 v9, v0
	v_mov_b32_e32 v10, v0
	v_mov_b32_e32 v11, v0
	v_mov_b32_e32 v12, v0
	v_mov_b32_e32 v13, v0
	v_mov_b32_e32 v14, v0
	v_mov_b32_e32 v15, v0
	v_mov_b32_e32 v16, v0
	v_mov_b32_e32 v17, v0
	v_mov_b32_e32 v18, v0
	v_mov_b32_e32 v19, v0
	v_mov_b32_e32 v20, v0
	v_mov_b32_e32 v21, v0
	v_mov_b32_e32 v22, v0
	v_mov_b32_e32 v23, v0
	v_mov_b32_e32 v24, v0
	v_mov_b32_e32 v25, v0
	v_mov_b32_e32 v26, v0
	v_mov_b32_e32 v27, v0
	v_mov_b32_e32 v28, v0
	v_mov_b32_e32 v29, v0
	v_mov_b32_e32 v30, v0
	v_mov_b32_e32 v31, v0
	v_mov_b32_e32 v66, v0
	v_mov_b32_e32 v67, v0
	v_mov_b32_e32 v68, v0
	v_mov_b32_e32 v69, v0
	v_mov_b32_e32 v70, v0
	v_mov_b32_e32 v71, v0
	v_mov_b32_e32 v72, v0
	v_mov_b32_e32 v73, v0
	v_mov_b32_e32 v74, v0
	v_mov_b32_e32 v75, v0
	v_mov_b32_e32 v76, v0
	v_mov_b32_e32 v77, v0
	v_mov_b32_e32 v78, v0
	v_mov_b32_e32 v79, v0
	v_mov_b32_e32 v80, v0
	v_mov_b32_e32 v81, v0
	v_mov_b32_e32 v82, v0
	v_mov_b32_e32 v83, v0
	v_mov_b32_e32 v84, v0
	v_mov_b32_e32 v85, v0
	v_mov_b32_e32 v86, v0
	v_mov_b32_e32 v87, v0
	v_mov_b32_e32 v88, v0
	v_mov_b32_e32 v89, v0
	v_mov_b32_e32 v90, v0
	v_mov_b32_e32 v91, v0
	v_mov_b32_e32 v92, v0
	v_mov_b32_e32 v93, v0
	v_mov_b32_e32 v94, v0
	v_mov_b32_e32 v95, v0
	v_mov_b32_e32 v96, v0
	v_mov_b32_e32 v97, v0
	v_mov_b32_e32 v32, v0
	v_mov_b32_e32 v33, v0
	v_mov_b32_e32 v34, v0
	v_mov_b32_e32 v35, v0
	v_mov_b32_e32 v36, v0
	v_mov_b32_e32 v37, v0
	v_mov_b32_e32 v38, v0
	v_mov_b32_e32 v39, v0
	v_mov_b32_e32 v40, v0
	v_mov_b32_e32 v41, v0
	v_mov_b32_e32 v42, v0
	v_mov_b32_e32 v43, v0
	v_mov_b32_e32 v44, v0
	v_mov_b32_e32 v45, v0
	v_mov_b32_e32 v46, v0
	v_mov_b32_e32 v47, v0
	v_mov_b32_e32 v48, v0
	v_mov_b32_e32 v49, v0
	v_mov_b32_e32 v50, v0
	v_mov_b32_e32 v51, v0
	v_mov_b32_e32 v52, v0
	v_mov_b32_e32 v53, v0
	v_mov_b32_e32 v54, v0
	v_mov_b32_e32 v55, v0
	v_mov_b32_e32 v56, v0
	v_mov_b32_e32 v57, v0
	v_mov_b32_e32 v58, v0
	v_mov_b32_e32 v59, v0
	v_mov_b32_e32 v60, v0
	v_mov_b32_e32 v61, v0
	v_mov_b32_e32 v62, v0
	v_mov_b32_e32 v63, v0
	v_mov_b32_e32 v98, v0
	v_mov_b32_e32 v99, v0
	v_mov_b32_e32 v100, v0
	v_mov_b32_e32 v101, v0
	v_mov_b32_e32 v102, v0
	v_mov_b32_e32 v103, v0
	v_mov_b32_e32 v104, v0
	v_mov_b32_e32 v105, v0
	v_mov_b32_e32 v106, v0
	v_mov_b32_e32 v107, v0
	v_mov_b32_e32 v108, v0
	v_mov_b32_e32 v109, v0
	v_mov_b32_e32 v110, v0
	v_mov_b32_e32 v111, v0
	v_mov_b32_e32 v112, v0
	v_mov_b32_e32 v113, v0
	v_mov_b32_e32 v114, v0
	v_mov_b32_e32 v115, v0
	v_mov_b32_e32 v116, v0
	v_mov_b32_e32 v117, v0
	v_mov_b32_e32 v118, v0
	v_mov_b32_e32 v119, v0
	v_mov_b32_e32 v120, v0
	v_mov_b32_e32 v121, v0
	v_mov_b32_e32 v122, v0
	v_mov_b32_e32 v123, v0
	v_mov_b32_e32 v124, v0
	v_mov_b32_e32 v125, v0
	v_mov_b32_e32 v126, v0
	v_mov_b32_e32 v127, v0
	v_mov_b32_e32 v128, v0
	v_mov_b32_e32 v129, v0
	s_barrier

.LBB0_1143:
	v_ashrrev_i32_e32 v17, 6, v14
	s_sext_i32_i16 s23, s8
	s_add_u32 s8, s78, 0x28c00000
	v_and_b32_e32 v15, 15, v14
	v_lshlrev_b32_e32 v19, 10, v17
	s_addc_u32 s9, s79, 0
	v_lshl_or_b32 v65, s11, 6, v15
	v_lshl_add_u32 v19, s11, 13, v19
	s_lshl_b32 s11, s10, 5
	s_and_b32 s18, s11, 0x60
	s_add_i32 m0, s62, 0x18000
	v_lshl_add_u64 v[6:7], v[6:7], 0, s[96:97]
	s_lshr_b32 s11, s18, 3
	global_load_lds_dwordx4 v[6:7], off
	v_lshl_add_u64 v[4:5], v[4:5], 0, s[96:97]
	s_add_i32 m0, s62, 0x1a000
	s_add_i32 s66, s62, 0x8000
	s_add_i32 s69, s62, 0xa000
	global_load_lds_dwordx4 v[4:5], off
	v_lshl_add_u64 v[0:1], v[0:1], 0, s[96:97]
	s_mov_b32 m0, s66
	s_add_u32 s16, s44, 0x80080
	global_load_lds_dwordx4 v[0:1], off
	v_lshl_add_u64 v[0:1], v[2:3], 0, s[96:97]
	s_mov_b32 m0, s69
	s_addc_u32 s17, s45, 0
	global_load_lds_dwordx4 v[0:1], off
	s_add_i32 m0, s62, 0x1c000
	v_lshl_add_u64 v[0:1], s[16:17], 0, v[134:135]
	global_load_lds_dwordx4 v[0:1], off
	v_lshl_add_u64 v[0:1], s[16:17], 0, v[130:131]
	s_add_i32 m0, s62, 0x1e000
	v_ashrrev_i32_e32 v16, 1, v14
	global_load_lds_dwordx4 v[0:1], off
	s_waitcnt vmcnt(8)
	s_barrier
	v_lshlrev_b32_e32 v0, 15, v11
	v_and_b32_e32 v0, 0xffff0000, v0
	v_lshl_add_u32 v0, v12, 12, v0
	v_and_b32_e32 v1, 1, v11
	v_lshl_or_b32 v0, v1, 6, v0
	v_lshl_add_u32 v138, v13, 1, v0
	v_lshlrev_b32_e32 v0, 15, v8
	v_and_b32_e32 v18, 48, v14
	v_lshlrev_b32_e32 v14, 2, v14
	v_and_b32_e32 v0, 0xffff0000, v0
	v_lshl_or_b32 v15, v15, 6, v18
	v_and_b32_e32 v14, 32, v14
	s_waitcnt vmcnt(6)
	v_lshl_add_u32 v0, v9, 12, v0
	v_and_b32_e32 v1, 1, v8
	v_and_b32_e32 v16, -8, v16
	v_bitop3_b32 v18, v15, v19, v14 bitop3:0xde
	v_add_lshl_u32 v17, s11, v17, 10
	s_cmp_lt_u32 s10, 4
	v_lshl_or_b32 v0, v1, 6, v0
	v_bitop3_b32 v144, v17, v15, v14 bitop3:0xf6
	s_cselect_b64 s[10:11], -1, 0
	v_add_u32_e32 v145, s18, v16
	s_ashr_i32 s70, s33, 31
	v_mov_b32_e32 v139, v64
	v_lshl_add_u32 v140, v10, 1, v0
	v_mov_b32_e32 v141, v64
	s_mov_b32 s73, 0
	v_add_u32_e32 v146, 0, v18
	s_movk_i32 s12, 0x2c00
	s_barrier
	s_branch .LBB0_1146

.LBB0_1313:
	v_ashrrev_i32_e32 v17, 6, v16
	s_add_u32 s61, s12, 0x10a000
	v_lshlrev_b32_e32 v19, 10, v17
	s_addc_u32 s62, s13, 0
	s_lshl_b32 s63, s11, 6
	v_lshl_add_u32 v19, s11, 13, v19
	s_lshl_b32 s11, s10, 5
	s_and_b32 s64, s11, 0x60
	s_add_i32 m0, s55, 0x18000
	v_lshl_add_u64 v[6:7], v[6:7], 0, s[96:97]
	s_lshr_b32 s11, s64, 3
	global_load_lds_dwordx4 v[6:7], off
	v_lshl_add_u64 v[4:5], v[4:5], 0, s[96:97]
	s_add_i32 m0, s55, 0x1a000
	s_add_i32 s65, s55, 0x8000
	s_add_i32 s66, s55, 0xa000
	s_sext_i32_i8 s82, s16
	global_load_lds_dwordx4 v[4:5], off
	v_lshl_add_u64 v[0:1], v[0:1], 0, s[96:97]
	s_mov_b32 m0, s65
	s_add_u32 s16, s22, 0x160080
	global_load_lds_dwordx4 v[0:1], off
	v_lshl_add_u64 v[0:1], v[2:3], 0, s[96:97]
	s_mov_b32 m0, s66
	s_addc_u32 s17, s23, 0
	global_load_lds_dwordx4 v[0:1], off
	s_add_i32 m0, s55, 0x1c000
	v_lshl_add_u64 v[0:1], s[16:17], 0, v[160:161]
	global_load_lds_dwordx4 v[0:1], off
	v_lshl_add_u64 v[0:1], s[16:17], 0, v[176:177]
	s_add_i32 m0, s55, 0x1e000
	s_mov_b32 s14, 0x16000
	global_load_lds_dwordx4 v[0:1], off
	s_waitcnt vmcnt(8)
	s_barrier
	v_lshrrev_b32_e32 v1, 1, v8
	v_mul_lo_u32 v0, v10, s29
	v_mad_u64_u32 v[0:1], s[16:17], v1, s14, v[0:1]
	v_or_b32_e32 v0, v0, v9
	v_add_lshl_u32 v0, v0, v11, 1
	v_mov_b32_e32 v1, v64
	s_mov_b64 s[18:19], 0x160080
	v_lshl_add_u64 v[178:179], v[0:1], 0, s[18:19]
	v_lshrrev_b32_e32 v1, 1, v12
	v_mul_lo_u32 v0, v14, s29
	v_ashrrev_i32_e32 v65, 4, v16
	v_and_b32_e32 v199, 15, v16
	v_and_b32_e32 v18, 48, v16
	v_lshlrev_b32_e32 v16, 2, v16
	v_mad_u64_u32 v[0:1], s[16:17], v1, s14, v[0:1]
	v_lshl_or_b32 v18, v199, 6, v18
	v_and_b32_e32 v16, 32, v16
	s_waitcnt vmcnt(6)
	v_or_b32_e32 v0, v0, v13
	v_bitop3_b32 v19, v18, v19, v16 bitop3:0xde
	v_add_lshl_u32 v17, s11, v17, 10
	s_cmp_lt_u32 s10, 4
	v_add_lshl_u32 v0, v0, v15, 1
	v_mov_b32_e32 v1, v64
	v_bitop3_b32 v208, v17, v18, v16 bitop3:0xf6
	s_cselect_b64 s[10:11], -1, 0
	s_ashr_i32 s69, s72, 31
	v_lshl_add_u64 v[180:181], v[0:1], 0, s[18:19]
	s_mov_b32 s70, 0
	v_add_u32_e32 v225, 0, v19
	s_barrier
	s_branch .LBB0_1316

.LBB0_1336:
	v_ashrrev_i32_e32 v16, 6, v65
	v_lshlrev_b32_e32 v18, 10, v16
	s_lshl_b32 s48, s18, 6
	v_lshl_add_u32 v18, s18, 13, v18
	s_lshl_b32 s18, s25, 5
	s_and_b32 s24, s18, 0x60
	s_add_i32 m0, s38, 0x18000
	v_lshl_add_u64 v[6:7], v[6:7], 0, s[96:97]
	s_lshr_b32 s18, s24, 3
	global_load_lds_dwordx4 v[6:7], off
	v_lshl_add_u64 v[4:5], v[4:5], 0, s[96:97]
	s_add_i32 m0, s38, 0x1a000
	s_add_i32 s49, s38, 0x8000
	s_add_i32 s54, s38, 0xa000
	global_load_lds_dwordx4 v[4:5], off
	v_lshl_add_u64 v[2:3], v[2:3], 0, s[96:97]
	s_mov_b32 m0, s49
	s_add_u32 s22, s8, 0x160080
	global_load_lds_dwordx4 v[2:3], off
	v_lshl_add_u64 v[0:1], v[0:1], 0, s[96:97]
	s_mov_b32 m0, s54
	s_addc_u32 s23, s9, 0
	global_load_lds_dwordx4 v[0:1], off
	s_add_i32 m0, s38, 0x1c000
	v_lshl_add_u64 v[0:1], s[22:23], 0, v[132:133]
	global_load_lds_dwordx4 v[0:1], off
	v_lshl_add_u64 v[0:1], s[22:23], 0, v[136:137]
	s_add_i32 m0, s38, 0x1e000
	v_add_lshl_u32 v16, s18, v16, 10
	global_load_lds_dwordx4 v[0:1], off
	s_waitcnt vmcnt(8)
	s_barrier
	s_bfe_u32 s18, s19, 0x10006
	s_mul_i32 s18, s18, 0x1600000
	s_mul_i32 s20, s20, 0x2c0000
	s_add_i32 s18, s18, s20
	s_add_u32 s18, s78, s18
	s_addc_u32 s19, s79, 0
	v_lshrrev_b32_e32 v1, 1, v8
	v_mul_lo_u32 v0, v10, s29
	s_mov_b32 s14, 0x16000
	s_add_u32 s16, s18, s16
	v_mad_u64_u32 v[0:1], s[22:23], v1, s14, v[0:1]
	s_addc_u32 s17, s19, s17
	v_or_b32_e32 v0, v0, v9
	s_add_u32 s16, s16, 0x2e560080
	v_add_lshl_u32 v0, v0, v11, 1
	v_mov_b32_e32 v1, v64
	s_addc_u32 s17, s17, 0
	v_lshl_add_u64 v[138:139], s[16:17], 0, v[0:1]
	v_lshrrev_b32_e32 v1, 1, v12
	v_mul_lo_u32 v0, v14, s29
	v_mad_u64_u32 v[0:1], s[18:19], v1, s14, v[0:1]
	v_and_b32_e32 v142, 15, v65
	v_and_b32_e32 v17, 48, v65
	v_lshlrev_b32_e32 v19, 2, v65
	v_or_b32_e32 v0, v0, v13
	v_lshl_or_b32 v17, v142, 6, v17
	v_and_b32_e32 v19, 32, v19
	s_waitcnt vmcnt(6)
	v_add_lshl_u32 v0, v0, v15, 1
	v_mov_b32_e32 v1, v64
	v_bitop3_b32 v18, v17, v18, v19 bitop3:0xde
	v_lshl_add_u64 v[140:141], s[16:17], 0, v[0:1]
	v_mov_b32_e32 v0, 0
	v_bitop3_b32 v143, v16, v17, v19 bitop3:0xf6
	s_mov_b32 s55, -2
	s_mov_b64 s[16:17], 0
	v_add_u32_e32 v144, 0, v18
	v_mov_b32_e32 v1, v0
	v_mov_b32_e32 v2, v0
	v_mov_b32_e32 v3, v0
	v_mov_b32_e32 v4, v0
	v_mov_b32_e32 v5, v0
	v_mov_b32_e32 v6, v0
	v_mov_b32_e32 v7, v0
	v_mov_b32_e32 v8, v0
	v_mov_b32_e32 v9, v0
	v_mov_b32_e32 v10, v0
	v_mov_b32_e32 v11, v0
	v_mov_b32_e32 v12, v0
	v_mov_b32_e32 v13, v0
	v_mov_b32_e32 v14, v0
	v_mov_b32_e32 v15, v0
	v_mov_b32_e32 v16, v0
	v_mov_b32_e32 v17, v0
	v_mov_b32_e32 v18, v0
	v_mov_b32_e32 v19, v0
	v_mov_b32_e32 v20, v0
	v_mov_b32_e32 v21, v0
	v_mov_b32_e32 v22, v0
	v_mov_b32_e32 v23, v0
	v_mov_b32_e32 v24, v0
	v_mov_b32_e32 v25, v0
	v_mov_b32_e32 v26, v0
	v_mov_b32_e32 v27, v0
	v_mov_b32_e32 v28, v0
	v_mov_b32_e32 v29, v0
	v_mov_b32_e32 v30, v0
	v_mov_b32_e32 v31, v0
	v_mov_b32_e32 v66, v0
	v_mov_b32_e32 v67, v0
	v_mov_b32_e32 v68, v0
	v_mov_b32_e32 v69, v0
	v_mov_b32_e32 v70, v0
	v_mov_b32_e32 v71, v0
	v_mov_b32_e32 v72, v0
	v_mov_b32_e32 v73, v0
	v_mov_b32_e32 v74, v0
	v_mov_b32_e32 v75, v0
	v_mov_b32_e32 v76, v0
	v_mov_b32_e32 v77, v0
	v_mov_b32_e32 v78, v0
	v_mov_b32_e32 v79, v0
	v_mov_b32_e32 v80, v0
	v_mov_b32_e32 v81, v0
	v_mov_b32_e32 v82, v0
	v_mov_b32_e32 v83, v0
	v_mov_b32_e32 v84, v0
	v_mov_b32_e32 v85, v0
	v_mov_b32_e32 v86, v0
	v_mov_b32_e32 v87, v0
	v_mov_b32_e32 v88, v0
	v_mov_b32_e32 v89, v0
	v_mov_b32_e32 v90, v0
	v_mov_b32_e32 v91, v0
	v_mov_b32_e32 v92, v0
	v_mov_b32_e32 v93, v0
	v_mov_b32_e32 v94, v0
	v_mov_b32_e32 v95, v0
	v_mov_b32_e32 v96, v0
	v_mov_b32_e32 v97, v0
	v_mov_b32_e32 v32, v0
	v_mov_b32_e32 v33, v0
	v_mov_b32_e32 v34, v0
	v_mov_b32_e32 v35, v0
	v_mov_b32_e32 v36, v0
	v_mov_b32_e32 v37, v0
	v_mov_b32_e32 v38, v0
	v_mov_b32_e32 v39, v0
	v_mov_b32_e32 v40, v0
	v_mov_b32_e32 v41, v0
	v_mov_b32_e32 v42, v0
	v_mov_b32_e32 v43, v0
	v_mov_b32_e32 v44, v0
	v_mov_b32_e32 v45, v0
	v_mov_b32_e32 v46, v0
	v_mov_b32_e32 v47, v0
	v_mov_b32_e32 v48, v0
	v_mov_b32_e32 v49, v0
	v_mov_b32_e32 v50, v0
	v_mov_b32_e32 v51, v0
	v_mov_b32_e32 v52, v0
	v_mov_b32_e32 v53, v0
	v_mov_b32_e32 v54, v0
	v_mov_b32_e32 v55, v0
	v_mov_b32_e32 v56, v0
	v_mov_b32_e32 v57, v0
	v_mov_b32_e32 v58, v0
	v_mov_b32_e32 v59, v0
	v_mov_b32_e32 v60, v0
	v_mov_b32_e32 v61, v0
	v_mov_b32_e32 v62, v0
	v_mov_b32_e32 v63, v0
	v_mov_b32_e32 v98, v0
	v_mov_b32_e32 v99, v0
	v_mov_b32_e32 v100, v0
	v_mov_b32_e32 v101, v0
	v_mov_b32_e32 v102, v0
	v_mov_b32_e32 v103, v0
	v_mov_b32_e32 v104, v0
	v_mov_b32_e32 v105, v0
	v_mov_b32_e32 v106, v0
	v_mov_b32_e32 v107, v0
	v_mov_b32_e32 v108, v0
	v_mov_b32_e32 v109, v0
	v_mov_b32_e32 v110, v0
	v_mov_b32_e32 v111, v0
	v_mov_b32_e32 v112, v0
	v_mov_b32_e32 v113, v0
	v_mov_b32_e32 v114, v0
	v_mov_b32_e32 v115, v0
	v_mov_b32_e32 v116, v0
	v_mov_b32_e32 v117, v0
	v_mov_b32_e32 v118, v0
	v_mov_b32_e32 v119, v0
	v_mov_b32_e32 v120, v0
	v_mov_b32_e32 v121, v0
	v_mov_b32_e32 v122, v0
	v_mov_b32_e32 v123, v0
	v_mov_b32_e32 v124, v0
	v_mov_b32_e32 v125, v0
	v_mov_b32_e32 v126, v0
	v_mov_b32_e32 v127, v0
	v_mov_b32_e32 v128, v0
	v_mov_b32_e32 v129, v0
	s_barrier
